# dilated chunks take units at stride 3072 so that units sharing a K/V tile run concurrently on one XCD (L2 reuse)
# baseline (speedup 1.0000x reference)
.LBB0_493:
	s_or_b64 exec, exec, s[82:83]
	v_readfirstlane_b32 s14, v0
	s_cmpk_gt_u32 s14, 0xbff
	s_mov_b64 s[82:83], -1
	s_cbranch_scc1 .LBB0_488
	s_add_i32 s8, s14, s60
	s_lshr_b32 s33, s8, 8
	s_mul_i32 s34, s33, 0xaaab
	s_lshr_b32 s34, s34, 17
	s_mul_i32 s34, s34, 3
	s_sub_i32 s33, s33, s34
	s_and_b32 s83, s33, 0xffff
	s_lshl_b32 s62, s83, 1
	s_lshr_b32 s34, 0x100, s62
	s_and_b32 s15, s14, 0xff
	s_sub_i32 s33, 8, s62
	s_add_i32 s34, s34, -1
	s_mul_hi_u32 s8, s8, 0xaaaaaaab
	s_lshr_b32 s33, s15, s33
	s_and_b32 s15, s34, s15
	s_bfe_u32 s82, s8, 0x30009
	s_lshl_b32 s15, s15, 5
	s_lshl_b32 s8, s8, 1
	s_and_b32 s48, s8, 0x3e000
	v_or_b32_e32 v184, s15, v162
	v_mov_b32_e32 v185, v167
	v_lshlrev_b64 v[0:1], s62, v[184:185]
	s_or_b32 s8, s33, s48
	s_add_i32 s34, s82, 1
	v_lshlrev_b32_e32 v2, s62, v168
	v_lshl_add_u64 v[182:183], v[0:1], 0, s[8:9]
	v_cvt_f32_ubyte0_e32 v0, s34
	s_lshl_b32 s34, 1, s62
	v_add_u32_e32 v2, s8, v2
	v_mov_b32_e32 v3, v167
	s_and_b32 s92, s15, 0x1fc0
	v_exp_f32_e64 v12, -v0
	v_cvt_f32_u32_e32 v13, s34
	v_lshlrev_b64 v[0:1], 12, v[182:183]
	s_lshl_b32 s34, s82, 7
	v_lshlrev_b64 v[2:3], 12, v[2:3]
	v_lshl_add_u64 v[0:1], s[22:23], 0, v[0:1]
	s_mov_b32 s35, s9
	v_lshl_add_u64 v[2:3], s[22:23], 0, v[2:3]
	s_cmp_eq_u32 s83, 1
	v_lshl_add_u64 v[0:1], v[0:1], 0, s[34:35]
	v_lshl_add_u64 v[2:3], v[2:3], 0, s[34:35]
	s_cselect_b32 s8, s20, s26
	s_cselect_b32 s34, s21, s27
	s_cmp_eq_u32 s83, 0
	s_cselect_b32 s34, s54, s34
	s_cselect_b32 s8, s49, s8
	v_lshl_or_b32 v8, s82, 6, v164
	v_mov_b32_e32 v6, s8
	v_mov_b32_e32 v7, s34
	v_mul_i32_i24_e32 v8, 0x18000, v8
	v_mov_b32_e32 v9, v167
	v_lshl_add_u64 v[6:7], v[8:9], 1, v[6:7]
	s_lshl_b32 s8, s48, 1
	v_lshl_add_u64 v[6:7], v[6:7], 0, s[8:9]
	s_sub_i32 s8, 13, s62
	s_lshl_b32 s8, s33, s8
	s_mov_b32 s93, s9
	s_lshl_b32 s8, s8, 1
	s_lshl_b64 s[34:35], s[92:93], s62
	v_lshl_add_u64 v[4:5], v[2:3], 0, v[178:179]
	v_lshl_add_u64 v[6:7], v[6:7], 0, s[8:9]
	s_lshl_b64 s[34:35], s[34:35], 12
	v_lshl_add_u64 v[52:53], v[6:7], 0, v[178:179]
	v_lshl_add_u64 v[54:55], v[6:7], 0, v[180:181]
	v_lshl_add_u64 v[6:7], v[4:5], 0, s[34:35]
	s_or_b32 s34, s92, 4
	s_mov_b32 s35, s9
	s_lshl_b64 s[34:35], s[34:35], s62
	v_lshl_add_u64 v[2:3], v[2:3], 0, v[180:181]
	s_lshl_b64 s[34:35], s[34:35], 12
	s_lshl_b32 s8, s92, 1
	v_lshl_add_u64 v[8:9], v[2:3], 0, s[34:35]
	global_load_dwordx4 v[64:67], v[6:7], off offset:3072
	global_load_dwordx4 v[72:75], v[8:9], off offset:3072
	v_lshl_add_u64 v[6:7], v[52:53], 0, s[8:9]
	v_lshl_add_u64 v[8:9], v[54:55], 0, s[8:9]
	s_or_b32 s8, s92, 16
	v_add_co_u32_e32 v10, vcc, s1, v8
	s_lshl_b64 s[34:35], s[8:9], s62
	s_nop 0
	v_addc_co_u32_e32 v11, vcc, 0, v9, vcc
	s_lshl_b64 s[34:35], s[34:35], 12
	global_load_dwordx4 v[76:79], v[10:11], off
	v_lshl_add_u64 v[10:11], v[4:5], 0, s[34:35]
	s_or_b32 s8, s92, 20
	global_load_dwordx4 v[80:83], v[10:11], off offset:3072
	v_add_co_u32_e32 v10, vcc, s52, v6
	s_lshl_b64 s[34:35], s[8:9], s62
	s_nop 0
	v_addc_co_u32_e32 v11, vcc, 0, v7, vcc
	s_lshl_b64 s[34:35], s[34:35], 12
	global_load_dwordx4 v[84:87], v[10:11], off
	v_lshl_add_u64 v[10:11], v[2:3], 0, s[34:35]
	s_or_b32 s8, s15, 32
	global_load_dwordx4 v[88:91], v[10:11], off offset:3072
	v_add_co_u32_e32 v10, vcc, s53, v8
	s_lshl_b64 s[34:35], s[8:9], s62
	s_nop 0
	v_addc_co_u32_e32 v11, vcc, 0, v9, vcc
	s_lshl_b64 s[34:35], s[34:35], 12
	global_load_dwordx4 v[92:95], v[10:11], off
	v_lshl_add_u64 v[10:11], v[4:5], 0, s[34:35]
	s_or_b32 s8, s15, 36
	global_load_dwordx4 v[96:99], v[10:11], off offset:3072
	v_add_co_u32_e32 v10, vcc, s6, v6
	s_lshl_b64 s[34:35], s[8:9], s62
	s_nop 0
	v_addc_co_u32_e32 v11, vcc, 0, v7, vcc
	s_lshl_b64 s[34:35], s[34:35], 12
	s_or_b32 s8, s15, 48
	global_load_dwordx4 v[100:103], v[10:11], off
	v_lshl_add_u64 v[10:11], v[2:3], 0, s[34:35]
	s_lshl_b64 s[34:35], s[8:9], s62
	global_load_dwordx4 v[104:107], v[10:11], off offset:3072
	v_add_co_u32_e32 v10, vcc, s7, v8
	s_lshl_b64 s[34:35], s[34:35], 12
	s_or_b32 s8, s15, 52
	v_lshl_add_u64 v[50:51], v[4:5], 0, s[10:11]
	v_addc_co_u32_e32 v11, vcc, 0, v9, vcc
	v_lshl_add_u64 v[4:5], v[4:5], 0, s[34:35]
	s_lshl_b64 s[34:35], s[8:9], s62
	global_load_dwordx4 v[112:115], v[4:5], off offset:3072
	v_add_co_u32_e32 v4, vcc, s42, v6
	s_lshl_b64 s[34:35], s[34:35], 12
	v_lshl_add_u64 v[48:49], v[2:3], 0, s[10:11]
	v_addc_co_u32_e32 v5, vcc, 0, v7, vcc
	v_lshl_add_u64 v[2:3], v[2:3], 0, s[34:35]
	global_load_dwordx4 v[120:123], v[2:3], off offset:3072
	v_add_co_u32_e32 v2, vcc, 0xa80000, v8
	v_mov_b32_e32 v177, v167
	s_nop 0
	v_addc_co_u32_e32 v3, vcc, 0, v9, vcc
	v_lshl_add_u64 v[0:1], v[0:1], 0, v[176:177]
	global_load_dwordx4 v[68:71], v[6:7], off
	global_load_dwordx4 v[116:119], v[4:5], off
	global_load_dwordx4 v[108:111], v[10:11], off
	global_load_dwordx4 v[140:143], v[2:3], off
	global_load_dwordx4 v[136:139], v[0:1], off offset:2048
	global_load_dwordx4 v[132:135], v[0:1], off offset:2080
	global_load_dwordx4 v[128:131], v[0:1], off offset:2112
	global_load_dwordx4 v[124:127], v[0:1], off offset:2144
	v_mul_f32_e32 v0, 0x3fb8aa3b, v12
	s_mov_b32 s63, 0
	s_lshr_b32 s34, 0x2000, s62
	v_mul_f32_e32 v186, v0, v13
	s_add_i32 s14, s61, s14
	s_addk_i32 s14, 0xbff
	s_branch .LBB0_496

.LBB0_496:
	s_cmp_lg_u32 s63, 2
	s_cselect_b64 s[86:87], -1, 0
	s_cmp_gt_i32 s92, 63
	s_cselect_b64 s[96:97], -1, 0
	s_add_i32 s84, s92, 64
	s_cmp_lt_i32 s84, s34
	s_cselect_b64 s[88:89], -1, 0
	s_cmp_ge_i32 s84, s34
	s_cselect_b64 s[90:91], -1, 0
	s_cmp_lt_i32 s92, 64
	s_waitcnt vmcnt(19)
	ds_write_b128 v222, v[64:67]
	s_waitcnt vmcnt(7)
	ds_write_b128 v222, v[68:71] offset:8192
	ds_write_b128 v222, v[72:75] offset:1024
	ds_write_b128 v222, v[76:79] offset:9216
	ds_write_b128 v222, v[80:83] offset:2048
	ds_write_b128 v222, v[84:87] offset:10240
	ds_write_b128 v222, v[88:91] offset:3072
	ds_write_b128 v222, v[92:95] offset:11264
	ds_write_b128 v222, v[96:99] offset:4096
	ds_write_b128 v222, v[100:103] offset:12288
	ds_write_b128 v222, v[104:107] offset:5120
	s_waitcnt vmcnt(5)
	ds_write_b128 v222, v[108:111] offset:13312
	ds_write_b128 v222, v[112:115] offset:6144
	ds_write_b128 v222, v[116:119] offset:14336
	ds_write_b128 v222, v[120:123] offset:7168
	s_waitcnt vmcnt(4)
	ds_write_b128 v222, v[140:143] offset:15360
	s_cbranch_scc0 .LBB0_501
	s_and_b64 vcc, exec, s[90:91]
	s_cbranch_vccz .LBB0_502
	s_waitcnt vmcnt(0)
	v_mov_b64_e32 v[32:33], v[124:125]
	v_mov_b64_e32 v[36:37], v[128:129]
	v_mov_b64_e32 v[40:41], v[132:133]
	v_mov_b64_e32 v[44:45], v[136:137]
	s_andn2_b64 vcc, exec, s[86:87]
	v_mov_b64_e32 v[60:61], v[50:51]
	v_mov_b64_e32 v[62:63], v[48:49]
	v_mov_b64_e32 v[200:201], v[52:53]
	v_mov_b64_e32 v[202:203], v[54:55]
	v_mov_b64_e32 v[56:57], v[182:183]
	v_mov_b32_e32 v59, v186
	s_mov_b32 s94, s92
	s_mov_b32 s15, s62
	s_mov_b32 s48, s34
	v_mov_b32_e32 v58, v184
	s_mov_b32 s35, s83
	s_mov_b32 s33, s82
	v_mov_b64_e32 v[34:35], v[126:127]
	v_mov_b64_e32 v[38:39], v[130:131]
	v_mov_b64_e32 v[42:43], v[134:135]
	v_mov_b64_e32 v[46:47], v[138:139]
	s_cbranch_vccnz .LBB0_500
	s_mul_i32 s8, s63, 0xc00
	s_add_i32 s8, s8, s14
	s_lshr_b32 s15, s8, 8
	s_mul_hi_u32 s33, s15, 0x55555556
	s_mul_i32 s33, s33, 3
	s_sub_i32 s35, s15, s33
	s_lshl_b32 s15, s35, 1
	s_lshr_b32 s85, 0x100, s15
	s_and_b32 s48, s8, 0xff
	s_sub_i32 s56, 8, s15
	s_add_i32 s85, s85, -1
	s_mul_hi_u32 s8, s8, 0xaaaaaaab
	s_lshr_b32 s56, s48, s56
	s_and_b32 s48, s85, s48
	s_bfe_u32 s33, s8, 0x30009
	s_lshl_b32 s48, s48, 5
	s_lshl_b32 s8, s8, 1
	s_and_b32 s85, s8, 0xfe000
	v_or_b32_e32 v58, s48, v162
	v_mov_b32_e32 v59, v167
	v_lshlrev_b64 v[0:1], s15, v[58:59]
	s_or_b32 s8, s56, s85
	s_add_i32 s93, s33, 1
	s_and_b32 s94, s48, 0x1fc0
	v_lshl_add_u64 v[56:57], v[0:1], 0, s[8:9]
	v_cvt_f32_ubyte0_e32 v0, s93
	s_lshl_b32 s93, 1, s15
	s_lshl_b32 vcc_lo, s33, 7
	v_lshlrev_b32_e32 v2, s15, v168
	s_cmp_eq_u32 s35, 1
	v_cvt_f32_u32_e32 v13, s93
	v_add_u32_e32 v2, s8, v2
	s_cselect_b32 s8, s20, s26
	s_cselect_b32 s93, s21, s27
	s_cmp_eq_u32 s35, 0
	s_cselect_b32 s93, s54, s93
	s_cselect_b32 s8, s49, s8
	v_lshl_or_b32 v8, s33, 6, v164
	v_mov_b32_e32 v6, s8
	v_mov_b32_e32 v7, s93
	v_mul_i32_i24_e32 v8, 0x18000, v8
	v_mov_b32_e32 v9, v167
	v_mov_b32_e32 v3, v167
	v_lshl_add_u64 v[6:7], v[8:9], 1, v[6:7]
	s_lshl_b32 s8, s85, 1
	v_exp_f32_e64 v12, -v0
	v_lshlrev_b64 v[0:1], 12, v[56:57]
	v_lshlrev_b64 v[2:3], 12, v[2:3]
	v_lshl_add_u64 v[6:7], v[6:7], 0, s[8:9]
	s_sub_i32 s8, 13, s15
	v_lshl_add_u64 v[0:1], s[22:23], 0, v[0:1]
	s_mov_b32 vcc_hi, s9
	v_lshl_add_u64 v[2:3], s[22:23], 0, v[2:3]
	s_lshl_b32 s8, s56, s8
	s_mov_b32 s95, s9
	v_lshl_add_u64 v[0:1], v[0:1], 0, vcc
	v_lshl_add_u64 v[2:3], v[2:3], 0, vcc
	s_lshl_b32 s8, s8, 1
	s_lshl_b64 vcc, s[94:95], s15
	v_lshl_add_u64 v[4:5], v[2:3], 0, v[178:179]
	v_lshl_add_u64 v[6:7], v[6:7], 0, s[8:9]
	s_lshl_b64 vcc, vcc, 12
	v_lshl_add_u64 v[200:201], v[6:7], 0, v[178:179]
	v_lshl_add_u64 v[202:203], v[6:7], 0, v[180:181]
	v_lshl_add_u64 v[6:7], v[4:5], 0, vcc
	s_or_b32 vcc_lo, s94, 4
	s_mov_b32 vcc_hi, s9
	s_lshl_b64 vcc, vcc, s15
	v_lshl_add_u64 v[2:3], v[2:3], 0, v[180:181]
	s_lshl_b64 vcc, vcc, 12
	s_lshl_b32 s8, s94, 1
	v_lshl_add_u64 v[8:9], v[2:3], 0, vcc
	global_load_dwordx4 v[64:67], v[6:7], off offset:3072
	global_load_dwordx4 v[72:75], v[8:9], off offset:3072
	v_lshl_add_u64 v[8:9], v[202:203], 0, s[8:9]
	v_add_co_u32_e32 v10, vcc, s1, v8
	v_lshl_add_u64 v[6:7], v[200:201], 0, s[8:9]
	s_nop 0
	v_addc_co_u32_e32 v11, vcc, 0, v9, vcc
	s_or_b32 s8, s94, 16
	s_lshl_b64 vcc, s[8:9], s15
	s_lshl_b64 vcc, vcc, 12
	global_load_dwordx4 v[76:79], v[10:11], off
	v_lshl_add_u64 v[10:11], v[4:5], 0, vcc
	global_load_dwordx4 v[80:83], v[10:11], off offset:3072
	v_add_co_u32_e32 v10, vcc, s52, v6
	s_or_b32 s8, s94, 20
	s_nop 0
	v_addc_co_u32_e32 v11, vcc, 0, v7, vcc
	s_lshl_b64 vcc, s[8:9], s15
	s_lshl_b64 vcc, vcc, 12
	global_load_dwordx4 v[84:87], v[10:11], off
	v_lshl_add_u64 v[10:11], v[2:3], 0, vcc
	global_load_dwordx4 v[88:91], v[10:11], off offset:3072
	v_add_co_u32_e32 v10, vcc, s53, v8
	s_or_b32 s8, s48, 32
	s_nop 0
	v_addc_co_u32_e32 v11, vcc, 0, v9, vcc
	s_lshl_b64 vcc, s[8:9], s15
	s_lshl_b64 vcc, vcc, 12
	global_load_dwordx4 v[92:95], v[10:11], off
	v_lshl_add_u64 v[10:11], v[4:5], 0, vcc
	global_load_dwordx4 v[96:99], v[10:11], off offset:3072
	v_add_co_u32_e32 v10, vcc, s6, v6
	s_or_b32 s8, s48, 36
	s_nop 0
	v_addc_co_u32_e32 v11, vcc, 0, v7, vcc
	s_lshl_b64 vcc, s[8:9], s15
	s_lshl_b64 vcc, vcc, 12
	global_load_dwordx4 v[100:103], v[10:11], off
	v_lshl_add_u64 v[10:11], v[2:3], 0, vcc
	global_load_dwordx4 v[104:107], v[10:11], off offset:3072
	v_add_co_u32_e32 v10, vcc, s7, v8
	s_or_b32 s8, s48, 48
	s_nop 0
	v_addc_co_u32_e32 v11, vcc, 0, v9, vcc
	s_lshl_b64 vcc, s[8:9], s15
	s_lshl_b64 vcc, vcc, 12
	v_lshl_add_u64 v[60:61], v[4:5], 0, s[10:11]
	v_lshl_add_u64 v[4:5], v[4:5], 0, vcc
	global_load_dwordx4 v[112:115], v[4:5], off offset:3072
	v_add_co_u32_e32 v4, vcc, s42, v6
	s_or_b32 s8, s48, 52
	s_nop 0
	v_addc_co_u32_e32 v5, vcc, 0, v7, vcc
	s_lshl_b64 vcc, s[8:9], s15
	s_lshl_b64 vcc, vcc, 12
	v_lshl_add_u64 v[62:63], v[2:3], 0, s[10:11]
	v_lshl_add_u64 v[2:3], v[2:3], 0, vcc
	global_load_dwordx4 v[120:123], v[2:3], off offset:3072
	v_add_co_u32_e32 v2, vcc, 0xa80000, v8
	v_mov_b32_e32 v177, v167
	s_nop 0
	v_addc_co_u32_e32 v3, vcc, 0, v9, vcc
	v_lshl_add_u64 v[0:1], v[0:1], 0, v[176:177]
	global_load_dwordx4 v[68:71], v[6:7], off
	global_load_dwordx4 v[116:119], v[4:5], off
	global_load_dwordx4 v[108:111], v[10:11], off
	global_load_dwordx4 v[140:143], v[2:3], off
	global_load_dwordx4 v[44:47], v[0:1], off offset:2048
	global_load_dwordx4 v[40:43], v[0:1], off offset:2080
	global_load_dwordx4 v[36:39], v[0:1], off offset:2112
	global_load_dwordx4 v[32:35], v[0:1], off offset:2144
	v_mul_f32_e32 v0, 0x3fb8aa3b, v12
	s_lshr_b32 s48, 0x2000, s15
	v_mul_f32_e32 v59, v0, v13

.LBB0_506:
	v_sub_u32_e32 v228, v184, v169
	v_subrev_u32_e32 v208, s92, v228
	v_cvt_f32_i32_e32 v16, v208
	s_andn2_b64 vcc, exec, s[96:97]
	v_add_f32_e32 v14, -1.0, v16
	v_pk_add_f32 v[0:1], v[16:17], s[12:13] op_sel_hi:[0,1]
	v_pk_add_f32 v[2:3], v[16:17], s[24:25] op_sel_hi:[0,1]
	v_pk_add_f32 v[4:5], v[16:17], s[28:29] op_sel_hi:[0,1]
	v_pk_add_f32 v[6:7], v[16:17], s[30:31] op_sel_hi:[0,1]
	v_pk_add_f32 v[8:9], v[16:17], s[36:37] op_sel_hi:[0,1]
	v_pk_add_f32 v[10:11], v[16:17], s[38:39] op_sel_hi:[0,1]
	v_pk_add_f32 v[12:13], v[16:17], s[40:41] op_sel_hi:[0,1]
	v_and_b32_e32 v1, 0x7fffffff, v1
	v_and_b32_e32 v0, 0x7fffffff, v0
	v_and_b32_e32 v3, 0x7fffffff, v3
	v_and_b32_e32 v2, 0x7fffffff, v2
	v_and_b32_e32 v5, 0x7fffffff, v5
	v_and_b32_e32 v4, 0x7fffffff, v4
	v_and_b32_e32 v7, 0x7fffffff, v7
	v_and_b32_e32 v6, 0x7fffffff, v6
	v_and_b32_e32 v9, 0x7fffffff, v9
	v_and_b32_e32 v8, 0x7fffffff, v8
	v_and_b32_e32 v11, 0x7fffffff, v11
	v_and_b32_e32 v10, 0x7fffffff, v10
	v_and_b32_e32 v13, 0x7fffffff, v13
	v_and_b32_e32 v12, 0x7fffffff, v12
	v_and_b32_e32 v18, 0x7fffffff, v16
	v_and_b32_e32 v19, 0x7fffffff, v14
	v_pk_mul_f32 v[14:15], v[12:13], v[186:187] op_sel_hi:[1,0] neg_lo:[0,1] neg_hi:[0,1]
	v_pk_mul_f32 v[12:13], v[10:11], v[186:187] op_sel_hi:[1,0] neg_lo:[0,1] neg_hi:[0,1]
	v_pk_mul_f32 v[10:11], v[8:9], v[186:187] op_sel_hi:[1,0] neg_lo:[0,1] neg_hi:[0,1]
	v_pk_mul_f32 v[8:9], v[6:7], v[186:187] op_sel_hi:[1,0] neg_lo:[0,1] neg_hi:[0,1]
	v_pk_mul_f32 v[6:7], v[4:5], v[186:187] op_sel_hi:[1,0] neg_lo:[0,1] neg_hi:[0,1]
	v_pk_mul_f32 v[4:5], v[2:3], v[186:187] op_sel_hi:[1,0] neg_lo:[0,1] neg_hi:[0,1]
	v_pk_mul_f32 v[2:3], v[0:1], v[186:187] op_sel_hi:[1,0] neg_lo:[0,1] neg_hi:[0,1]
	v_pk_mul_f32 v[0:1], v[18:19], v[186:187] op_sel_hi:[1,0] neg_lo:[0,1] neg_hi:[0,1]
	v_pk_add_f32 v[18:19], v[16:17], s[64:65] op_sel_hi:[0,1]
	v_pk_add_f32 v[20:21], v[16:17], s[66:67] op_sel_hi:[0,1]
	v_pk_add_f32 v[22:23], v[16:17], s[68:69] op_sel_hi:[0,1]
	v_pk_add_f32 v[26:27], v[16:17], s[72:73] op_sel_hi:[0,1]
	v_pk_add_f32 v[28:29], v[16:17], s[74:75] op_sel_hi:[0,1]
	v_pk_add_f32 v[30:31], v[16:17], s[76:77] op_sel_hi:[0,1]
	v_and_b32_e32 v145, 0x7fffffff, v31
	v_and_b32_e32 v144, 0x7fffffff, v30
	v_and_b32_e32 v147, 0x7fffffff, v29
	v_and_b32_e32 v146, 0x7fffffff, v28
	v_and_b32_e32 v149, 0x7fffffff, v27
	v_and_b32_e32 v148, 0x7fffffff, v26
	v_and_b32_e32 v23, 0x7fffffff, v23
	v_and_b32_e32 v22, 0x7fffffff, v22
	v_and_b32_e32 v21, 0x7fffffff, v21
	v_and_b32_e32 v20, 0x7fffffff, v20
	v_and_b32_e32 v19, 0x7fffffff, v19
	v_and_b32_e32 v18, 0x7fffffff, v18
	v_pk_mul_f32 v[30:31], v[18:19], v[186:187] op_sel_hi:[1,0] neg_lo:[0,1] neg_hi:[0,1]
	v_pk_mul_f32 v[28:29], v[20:21], v[186:187] op_sel_hi:[1,0] neg_lo:[0,1] neg_hi:[0,1]
	v_pk_mul_f32 v[26:27], v[22:23], v[186:187] op_sel_hi:[1,0] neg_lo:[0,1] neg_hi:[0,1]
	v_pk_mul_f32 v[22:23], v[148:149], v[186:187] op_sel_hi:[1,0] neg_lo:[0,1] neg_hi:[0,1]
	v_pk_mul_f32 v[20:21], v[146:147], v[186:187] op_sel_hi:[1,0] neg_lo:[0,1] neg_hi:[0,1]
	v_pk_mul_f32 v[18:19], v[144:145], v[186:187] op_sel_hi:[1,0] neg_lo:[0,1] neg_hi:[0,1]
	ds_read_b128 v[144:147], v223
	ds_read_b128 v[148:151], v223 offset:4096
	v_pk_add_f32 v[24:25], v[16:17], s[70:71] op_sel_hi:[0,1]
	v_pk_add_f32 v[16:17], v[16:17], s[78:79] op_sel_hi:[0,1]
	v_and_b32_e32 v17, 0x7fffffff, v17
	v_and_b32_e32 v16, 0x7fffffff, v16
	v_and_b32_e32 v25, 0x7fffffff, v25
	v_and_b32_e32 v24, 0x7fffffff, v24
	v_pk_mul_f32 v[24:25], v[24:25], v[186:187] op_sel_hi:[1,0] neg_lo:[0,1] neg_hi:[0,1]
	v_pk_mul_f32 v[16:17], v[16:17], v[186:187] op_sel_hi:[1,0] neg_lo:[0,1] neg_hi:[0,1]
	s_waitcnt vmcnt(3) lgkmcnt(1)
	v_mfma_f32_32x32x16_bf16 v[0:15], v[144:147], v[136:139], v[0:15]
	s_waitcnt lgkmcnt(0)
	v_mfma_f32_32x32x16_bf16 v[16:31], v[148:151], v[136:139], v[16:31]
	ds_read_b128 v[144:147], v224
	ds_read_b128 v[148:151], v224 offset:4096
	s_waitcnt vmcnt(2) lgkmcnt(1)
	v_mfma_f32_32x32x16_bf16 v[0:15], v[144:147], v[132:135], v[0:15]
	s_waitcnt lgkmcnt(0)
	v_mfma_f32_32x32x16_bf16 v[16:31], v[148:151], v[132:135], v[16:31]
	ds_read_b128 v[144:147], v225
	ds_read_b128 v[148:151], v225 offset:4096
	s_waitcnt vmcnt(1) lgkmcnt(1)
	v_mfma_f32_32x32x16_bf16 v[0:15], v[144:147], v[128:131], v[0:15]
	s_waitcnt lgkmcnt(0)
	v_mfma_f32_32x32x16_bf16 v[16:31], v[148:151], v[128:131], v[16:31]
	ds_read_b128 v[144:147], v226
	ds_read_b128 v[148:151], v226 offset:4096
	s_waitcnt vmcnt(0) lgkmcnt(1)
	v_mfma_f32_32x32x16_bf16 v[0:15], v[144:147], v[124:127], v[0:15]
	s_waitcnt lgkmcnt(0)
	v_mfma_f32_32x32x16_bf16 v[16:31], v[148:151], v[124:127], v[16:31]
	s_nop 9
	v_max_f32_e32 v145, v1, v1
	v_max_f32_e32 v146, v2, v2
	v_max_f32_e32 v147, v3, v3
	v_max_f32_e32 v144, v17, v17
	v_max_f32_e32 v144, v145, v144
	v_max_f32_e32 v145, v18, v18
	v_max_f32_e32 v145, v146, v145
	v_max_f32_e32 v146, v19, v19
	v_max3_f32 v144, v0, v16, v144
	v_max_f32_e32 v146, v147, v146
	v_max3_f32 v144, v144, v145, v146
	v_max_f32_e32 v145, v20, v20
	v_max_f32_e32 v146, v4, v4
	v_max_f32_e32 v145, v146, v145
	v_max_f32_e32 v146, v21, v21
	v_max_f32_e32 v147, v5, v5
	v_max_f32_e32 v146, v147, v146
	v_max3_f32 v144, v144, v145, v146
	v_max_f32_e32 v145, v22, v22
	v_max_f32_e32 v146, v6, v6
	v_max_f32_e32 v145, v146, v145
	v_max_f32_e32 v146, v23, v23
	v_max_f32_e32 v147, v7, v7
	v_max_f32_e32 v146, v147, v146
	v_max3_f32 v144, v144, v145, v146
	v_max_f32_e32 v145, v24, v24
	v_max_f32_e32 v146, v8, v8
	v_max_f32_e32 v145, v146, v145
	v_max_f32_e32 v146, v25, v25
	v_max_f32_e32 v147, v9, v9
	v_max_f32_e32 v146, v147, v146
	v_max3_f32 v144, v144, v145, v146
	v_max_f32_e32 v145, v26, v26
	v_max_f32_e32 v146, v10, v10
	v_max_f32_e32 v145, v146, v145
	v_max_f32_e32 v146, v27, v27
	v_max_f32_e32 v147, v11, v11
	v_max_f32_e32 v146, v147, v146
	v_max3_f32 v144, v144, v145, v146
	v_max_f32_e32 v145, v28, v28
	v_max_f32_e32 v146, v12, v12
	v_max_f32_e32 v145, v146, v145
	v_max_f32_e32 v146, v29, v29
	v_max_f32_e32 v147, v13, v13
	v_max_f32_e32 v146, v147, v146
	v_max3_f32 v144, v144, v145, v146
	v_max_f32_e32 v145, v30, v30
	v_max_f32_e32 v146, v14, v14
	v_max_f32_e32 v145, v146, v145
	v_max_f32_e32 v146, v31, v31
	v_max_f32_e32 v147, v15, v15
	v_max_f32_e32 v146, v147, v146
	v_max3_f32 v144, v144, v145, v146
	v_mov_b32_e32 v145, v144
	s_nop 1
	v_permlane32_swap_b32 v144, v145
	s_nop 1
	ds_read_b128 v[234:237], v224 offset:8192
	v_max_f32_e32 v145, v145, v145
	v_max_f32_e32 v144, v144, v144
	v_max_f32_e32 v188, v144, v145
	v_sub_f32_e32 v0, v0, v188
	v_sub_f32_e32 v16, v16, v188
	v_sub_f32_e32 v1, v1, v188
	v_sub_f32_e32 v17, v17, v188
	v_exp_f32_e32 v184, v0
	v_exp_f32_e32 v185, v16
	v_sub_f32_e32 v2, v2, v188
	v_sub_f32_e32 v18, v18, v188
	v_exp_f32_e32 v190, v1
	v_exp_f32_e32 v191, v17
	v_sub_f32_e32 v3, v3, v188
	v_sub_f32_e32 v19, v19, v188
	v_exp_f32_e32 v192, v2
	v_exp_f32_e32 v193, v18
	v_sub_f32_e32 v4, v4, v188
	v_sub_f32_e32 v20, v20, v188
	v_exp_f32_e32 v194, v3
	v_exp_f32_e32 v195, v19
	v_sub_f32_e32 v5, v5, v188
	v_sub_f32_e32 v21, v21, v188
	v_pk_add_f32 v[0:1], v[184:185], 0 op_sel_hi:[1,0]
	v_exp_f32_e32 v196, v4
	v_exp_f32_e32 v197, v20
	v_sub_f32_e32 v6, v6, v188
	v_sub_f32_e32 v22, v22, v188
	v_pk_add_f32 v[0:1], v[190:191], v[0:1]
	v_exp_f32_e32 v198, v5
	v_exp_f32_e32 v199, v21
	v_sub_f32_e32 v7, v7, v188
	v_sub_f32_e32 v23, v23, v188
	v_pk_add_f32 v[0:1], v[192:193], v[0:1]
	v_exp_f32_e32 v204, v6
	v_exp_f32_e32 v205, v22
	v_sub_f32_e32 v8, v8, v188
	v_sub_f32_e32 v24, v24, v188
	v_pk_add_f32 v[0:1], v[194:195], v[0:1]
	v_exp_f32_e32 v206, v7
	v_exp_f32_e32 v207, v23
	v_sub_f32_e32 v9, v9, v188
	v_sub_f32_e32 v25, v25, v188
	v_exp_f32_e32 v144, v8
	v_exp_f32_e32 v145, v24
	v_pk_add_f32 v[0:1], v[196:197], v[0:1]
	v_sub_f32_e32 v10, v10, v188
	v_sub_f32_e32 v26, v26, v188
	v_exp_f32_e32 v146, v9
	v_exp_f32_e32 v147, v25
	v_pk_add_f32 v[0:1], v[198:199], v[0:1]
	v_sub_f32_e32 v11, v11, v188
	v_sub_f32_e32 v27, v27, v188
	v_exp_f32_e32 v148, v10
	v_exp_f32_e32 v149, v26
	v_pk_add_f32 v[0:1], v[204:205], v[0:1]
	v_sub_f32_e32 v12, v12, v188
	v_sub_f32_e32 v28, v28, v188
	v_exp_f32_e32 v150, v11
	v_exp_f32_e32 v151, v27
	v_pk_add_f32 v[0:1], v[206:207], v[0:1]
	v_sub_f32_e32 v13, v13, v188
	v_sub_f32_e32 v29, v29, v188
	v_exp_f32_e32 v152, v12
	v_exp_f32_e32 v153, v28
	v_pk_add_f32 v[0:1], v[144:145], v[0:1]
	v_sub_f32_e32 v14, v14, v188
	v_sub_f32_e32 v30, v30, v188
	v_exp_f32_e32 v154, v13
	v_exp_f32_e32 v155, v29
	v_pk_add_f32 v[0:1], v[146:147], v[0:1]
	ds_read_b128 v[4:7], v223 offset:8192
	v_sub_f32_e32 v15, v15, v188
	v_sub_f32_e32 v31, v31, v188
	v_exp_f32_e32 v156, v14
	v_exp_f32_e32 v157, v30
	v_pk_add_f32 v[0:1], v[148:149], v[0:1]
	v_exp_f32_e32 v158, v15
	v_exp_f32_e32 v159, v31
	v_pk_add_f32 v[0:1], v[150:151], v[0:1]
	v_cvt_pk_bf16_f32 v2, v196, v198
	v_pk_add_f32 v[0:1], v[152:153], v[0:1]
	v_cvt_pk_bf16_f32 v3, v204, v206
	v_pk_add_f32 v[0:1], v[154:155], v[0:1]
	v_cvt_pk_bf16_f32 v230, v144, v146
	v_pk_add_f32 v[0:1], v[156:157], v[0:1]
	v_cvt_pk_bf16_f32 v231, v148, v150
	v_pk_add_f32 v[0:1], v[158:159], v[0:1]
	v_cvt_pk_bf16_f32 v232, v152, v154
	v_pk_add_f32 v[0:1], v[0:1], v[0:1] op_sel_hi:[0,1]
	v_mov_b32_e32 v189, v1
	v_cvt_pk_bf16_f32 v0, v184, v190
	v_cvt_pk_bf16_f32 v1, v192, v194
	v_cvt_pk_bf16_f32 v233, v156, v158
	v_cvt_pk_bf16_f32 v190, v185, v191
	s_waitcnt lgkmcnt(0)
	v_mfma_f32_32x32x16_bf16 v[16:31], v[4:7], v[0:3], 0
	ds_read_b128 v[4:7], v223 offset:12288
	v_cvt_pk_bf16_f32 v191, v193, v195
	v_cvt_pk_bf16_f32 v192, v197, v199
	ds_read_b128 v[194:197], v225 offset:8192
	v_cvt_pk_bf16_f32 v193, v205, v207
	v_cvt_pk_bf16_f32 v144, v145, v147
	v_cvt_pk_bf16_f32 v145, v149, v151
	v_mfma_f32_32x32x16_bf16 v[16:31], v[234:237], v[230:233], v[16:31]
	ds_read_b128 v[234:237], v224 offset:12288
	ds_read_b128 v[148:151], v226 offset:8192
	v_cvt_pk_bf16_f32 v146, v153, v155
	v_cvt_pk_bf16_f32 v147, v157, v159
	v_add_f32_e64 v188, v188, 0
	v_add_f32_e64 v189, v189, 0
	s_waitcnt lgkmcnt(3)
	v_mfma_f32_32x32x16_bf16 v[0:15], v[4:7], v[0:3], 0
	s_waitcnt lgkmcnt(2)
	v_mfma_f32_32x32x16_bf16 v[16:31], v[194:197], v[190:193], v[16:31]
	ds_read_b128 v[194:197], v225 offset:12288
	s_waitcnt lgkmcnt(2)
	v_mfma_f32_32x32x16_bf16 v[0:15], v[234:237], v[230:233], v[0:15]
	s_waitcnt lgkmcnt(1)
	v_mfma_f32_32x32x16_bf16 v[16:31], v[148:151], v[144:147], v[16:31]
	ds_read_b128 v[148:151], v226 offset:12288
	s_waitcnt lgkmcnt(1)
	v_mfma_f32_32x32x16_bf16 v[0:15], v[194:197], v[190:193], v[0:15]
	s_waitcnt lgkmcnt(0)
	v_mfma_f32_32x32x16_bf16 v[0:15], v[148:151], v[144:147], v[0:15]
	s_cbranch_vccnz .LBB0_511
	s_and_b64 vcc, exec, s[90:91]
	ds_write_b128 v222, v[64:67]
	ds_write_b128 v222, v[68:71] offset:8192
	ds_write_b128 v222, v[72:75] offset:1024
	ds_write_b128 v222, v[76:79] offset:9216
	ds_write_b128 v222, v[80:83] offset:2048
	ds_write_b128 v222, v[84:87] offset:10240
	ds_write_b128 v222, v[88:91] offset:3072
	ds_write_b128 v222, v[92:95] offset:11264
	ds_write_b128 v222, v[96:99] offset:4096
	ds_write_b128 v222, v[100:103] offset:12288
	ds_write_b128 v222, v[104:107] offset:5120
	ds_write_b128 v222, v[108:111] offset:13312
	ds_write_b128 v222, v[112:115] offset:6144
	ds_write_b128 v222, v[116:119] offset:14336
	ds_write_b128 v222, v[120:123] offset:7168
	ds_write_b128 v222, v[140:143] offset:15360
	s_cbranch_vccz .LBB0_512
	v_mov_b64_e32 v[158:159], v[34:35]
	v_mov_b64_e32 v[154:155], v[38:39]
	v_mov_b64_e32 v[150:151], v[42:43]
	v_mov_b64_e32 v[146:147], v[46:47]
	s_andn2_b64 vcc, exec, s[86:87]
	v_mov_b64_e32 v[192:193], v[60:61]
	v_mov_b64_e32 v[194:195], v[62:63]
	v_mov_b64_e32 v[196:197], v[200:201]
	v_mov_b64_e32 v[198:199], v[202:203]
	v_mov_b64_e32 v[190:191], v[56:57]
	v_mov_b32_e32 v177, v59
	s_mov_b32 s90, s94
	s_mov_b32 s95, s15
	s_mov_b32 s34, s48
	v_mov_b32_e32 v184, v58
	s_mov_b32 s93, s35
	s_mov_b32 s56, s33
	v_mov_b64_e32 v[156:157], v[32:33]
	v_mov_b64_e32 v[152:153], v[36:37]
	v_mov_b64_e32 v[148:149], v[40:41]
	v_mov_b64_e32 v[144:145], v[44:45]
	s_cbranch_vccnz .LBB0_510
	s_mul_i32 s8, s63, 0xc00
	s_add_i32 s8, s8, s14
	s_lshr_b32 s56, s8, 8
	s_mul_hi_u32 s85, s56, 0x55555556
	s_mul_i32 s85, s85, 3
	s_sub_i32 s93, s56, s85
	s_lshl_b32 s95, s93, 1
	s_lshr_b32 s90, 0x100, s95
	s_and_b32 s34, s8, 0xff
	s_sub_i32 s85, 8, s95
	s_add_i32 s90, s90, -1
	s_mul_hi_u32 s8, s8, 0xaaaaaaab
	s_lshr_b32 s85, s34, s85
	s_and_b32 s34, s90, s34
	s_bfe_u32 s56, s8, 0x30009
	s_lshl_b32 s34, s34, 5
	s_lshl_b32 s8, s8, 1
	s_and_b32 s91, s8, 0xfe000
	v_or_b32_e32 v184, s34, v162
	v_mov_b32_e32 v185, v167
	v_lshlrev_b64 v[64:65], s95, v[184:185]
	s_or_b32 s8, s85, s91
	s_add_i32 s96, s56, 1
	v_lshl_add_u64 v[190:191], v[64:65], 0, s[8:9]
	v_cvt_f32_ubyte0_e32 v64, s96
	v_exp_f32_e64 v185, -v64
	s_lshl_b32 s96, 1, s95
	v_lshlrev_b64 v[64:65], 12, v[190:191]
	v_cvt_f32_u32_e32 v204, s96
	v_lshl_add_u64 v[64:65], s[22:23], 0, v[64:65]
	s_lshl_b32 s96, s56, 7
	s_mov_b32 s97, s9
	v_lshl_add_u64 v[64:65], v[64:65], 0, s[96:97]
	v_mov_b32_e32 v177, v167
	v_lshl_add_u64 v[156:157], v[64:65], 0, v[176:177]
	v_lshlrev_b32_e32 v64, s95, v168
	v_add_u32_e32 v64, s8, v64
	v_mov_b32_e32 v65, v167
	s_and_b32 s90, s34, 0x1fc0
	v_lshlrev_b64 v[64:65], 12, v[64:65]
	v_lshl_add_u64 v[64:65], s[22:23], 0, v[64:65]
	s_cmp_eq_u32 s93, 1
	v_lshl_add_u64 v[64:65], v[64:65], 0, s[96:97]
	s_cselect_b32 s8, s20, s26
	s_cselect_b32 s96, s21, s27
	s_cmp_eq_u32 s93, 0
	s_cselect_b32 s96, s54, s96
	s_cselect_b32 s8, s49, s8
	v_lshl_or_b32 v66, s56, 6, v164
	v_lshl_add_u64 v[112:113], v[64:65], 0, v[178:179]
	v_lshl_add_u64 v[120:121], v[64:65], 0, v[180:181]
	v_mov_b32_e32 v64, s8
	v_mov_b32_e32 v65, s96
	v_mul_i32_i24_e32 v66, 0x18000, v66
	v_mov_b32_e32 v67, v167
	v_lshl_add_u64 v[64:65], v[66:67], 1, v[64:65]
	s_lshl_b32 s8, s91, 1
	v_lshl_add_u64 v[64:65], v[64:65], 0, s[8:9]
	s_sub_i32 s8, 13, s95
	s_lshl_b32 s8, s85, s8
	s_mov_b32 s91, s9
	s_lshl_b32 s8, s8, 1
	s_lshl_b64 s[96:97], s[90:91], s95
	v_lshl_add_u64 v[64:65], v[64:65], 0, s[8:9]
	s_lshl_b64 s[96:97], s[96:97], 12
	v_lshl_add_u64 v[196:197], v[64:65], 0, v[178:179]
	v_lshl_add_u64 v[198:199], v[64:65], 0, v[180:181]
	v_lshl_add_u64 v[64:65], v[112:113], 0, s[96:97]
	s_lshl_b32 s8, s90, 1
	s_or_b32 s96, s90, 4
	s_mov_b32 s97, s9
	s_lshl_b64 s[96:97], s[96:97], s95
	v_lshl_add_u64 v[140:141], v[198:199], 0, s[8:9]
	v_lshl_add_u64 v[116:117], v[196:197], 0, s[8:9]
	s_lshl_b64 s[96:97], s[96:97], 12
	v_add_co_u32_e32 v76, vcc, s1, v140
	s_or_b32 s8, s90, 16
	v_lshl_add_u64 v[72:73], v[120:121], 0, s[96:97]
	v_addc_co_u32_e32 v77, vcc, 0, v141, vcc
	s_lshl_b64 s[96:97], s[8:9], s95
	s_lshl_b64 s[96:97], s[96:97], 12
	v_add_co_u32_e32 v84, vcc, s52, v116
	s_or_b32 s8, s90, 20
	v_lshl_add_u64 v[80:81], v[112:113], 0, s[96:97]
	v_addc_co_u32_e32 v85, vcc, 0, v117, vcc
	s_lshl_b64 s[96:97], s[8:9], s95
	s_lshl_b64 s[96:97], s[96:97], 12
	v_add_co_u32_e32 v92, vcc, s53, v140
	s_or_b32 s8, s34, 32
	v_lshl_add_u64 v[88:89], v[120:121], 0, s[96:97]
	v_addc_co_u32_e32 v93, vcc, 0, v141, vcc
	s_lshl_b64 s[96:97], s[8:9], s95
	s_lshl_b64 s[96:97], s[96:97], 12
	v_add_co_u32_e32 v100, vcc, s6, v116
	s_or_b32 s8, s34, 36
	v_lshl_add_u64 v[96:97], v[112:113], 0, s[96:97]
	v_addc_co_u32_e32 v101, vcc, 0, v117, vcc
	s_lshl_b64 s[96:97], s[8:9], s95
	s_lshl_b64 s[96:97], s[96:97], 12
	v_add_co_u32_e32 v108, vcc, s7, v140
	s_or_b32 s8, s34, 48
	v_lshl_add_u64 v[104:105], v[120:121], 0, s[96:97]
	v_addc_co_u32_e32 v109, vcc, 0, v141, vcc
	s_lshl_b64 s[96:97], s[8:9], s95
	global_load_dwordx4 v[68:71], v[116:117], off
	s_lshl_b64 s[96:97], s[96:97], 12
	v_add_co_u32_e32 v116, vcc, s42, v116
	s_or_b32 s8, s34, 52
	v_lshl_add_u64 v[192:193], v[112:113], 0, s[10:11]
	v_lshl_add_u64 v[112:113], v[112:113], 0, s[96:97]
	v_addc_co_u32_e32 v117, vcc, 0, v117, vcc
	s_lshl_b64 s[96:97], s[8:9], s95
	s_lshl_b64 s[96:97], s[96:97], 12
	v_add_co_u32_e32 v140, vcc, 0xa80000, v140
	v_lshl_add_u64 v[194:195], v[120:121], 0, s[10:11]
	v_lshl_add_u64 v[120:121], v[120:121], 0, s[96:97]
	v_addc_co_u32_e32 v141, vcc, 0, v141, vcc
	global_load_dwordx4 v[64:67], v[64:65], off offset:3072
	v_mul_f32_e32 v177, 0x3fb8aa3b, v185
	global_load_dwordx4 v[72:75], v[72:73], off offset:3072
	s_lshr_b32 s34, 0x2000, s95
	global_load_dwordx4 v[76:79], v[76:77], off
	v_mul_f32_e32 v177, v177, v204
	global_load_dwordx4 v[80:83], v[80:81], off offset:3072
	s_nop 0
	global_load_dwordx4 v[84:87], v[84:85], off
	s_nop 0
	global_load_dwordx4 v[88:91], v[88:89], off offset:3072
	s_nop 0
	global_load_dwordx4 v[92:95], v[92:93], off
	s_nop 0
	global_load_dwordx4 v[96:99], v[96:97], off offset:3072
	s_nop 0
	global_load_dwordx4 v[100:103], v[100:101], off
	s_nop 0
	global_load_dwordx4 v[104:107], v[104:105], off offset:3072
	s_nop 0
	global_load_dwordx4 v[108:111], v[108:109], off
	s_nop 0
	global_load_dwordx4 v[112:115], v[112:113], off offset:3072
	s_nop 0
	global_load_dwordx4 v[116:119], v[116:117], off
	s_nop 0
	global_load_dwordx4 v[120:123], v[120:121], off offset:3072
	s_nop 0
	global_load_dwordx4 v[140:143], v[140:141], off
	s_nop 0
	global_load_dwordx4 v[144:147], v[156:157], off offset:2048
	global_load_dwordx4 v[148:151], v[156:157], off offset:2080
	global_load_dwordx4 v[152:155], v[156:157], off offset:2112
	s_nop 0
	global_load_dwordx4 v[156:159], v[156:157], off offset:2144

.LBB0_517:
	s_andn2_b64 vcc, exec, s[86:87]
	s_waitcnt vmcnt(15)
	ds_write_b128 v222, v[64:67]
	s_waitcnt vmcnt(12)
	ds_write_b128 v222, v[68:71] offset:8192
	s_waitcnt vmcnt(11)
	ds_write_b128 v222, v[72:75] offset:1024
	s_waitcnt vmcnt(10)
	ds_write_b128 v222, v[76:79] offset:9216
	s_waitcnt vmcnt(9)
	ds_write_b128 v222, v[80:83] offset:2048
	s_waitcnt vmcnt(8)
	ds_write_b128 v222, v[84:87] offset:10240
	s_waitcnt vmcnt(7)
	ds_write_b128 v222, v[88:91] offset:3072
	s_waitcnt vmcnt(6)
	ds_write_b128 v222, v[92:95] offset:11264
	s_waitcnt vmcnt(5)
	ds_write_b128 v222, v[96:99] offset:4096
	s_waitcnt vmcnt(4)
	ds_write_b128 v222, v[100:103] offset:12288
	s_waitcnt vmcnt(3)
	ds_write_b128 v222, v[104:107] offset:5120
	s_waitcnt vmcnt(2)
	ds_write_b128 v222, v[108:111] offset:13312
	ds_write_b128 v222, v[112:115] offset:6144
	s_waitcnt vmcnt(1)
	ds_write_b128 v222, v[116:119] offset:14336
	ds_write_b128 v222, v[120:123] offset:7168
	s_waitcnt vmcnt(0)
	ds_write_b128 v222, v[140:143] offset:15360
	s_cbranch_vccnz .LBB0_519
	s_mul_i32 s8, s63, 0xc00
	s_add_i32 s8, s8, s14
	s_lshr_b32 s33, s8, 8
	s_mul_hi_u32 s34, s33, 0x55555556
	s_mul_i32 s34, s34, 3
	s_sub_i32 s93, s33, s34
	s_lshl_b32 s95, s93, 1
	s_lshr_b32 s34, 0x100, s95
	s_and_b32 s15, s8, 0xff
	s_sub_i32 s33, 8, s95
	s_add_i32 s34, s34, -1
	s_mul_hi_u32 s8, s8, 0xaaaaaaab
	s_lshr_b32 s33, s15, s33
	s_and_b32 s15, s34, s15
	s_bfe_u32 s56, s8, 0x30009
	s_lshl_b32 s15, s15, 5
	s_lshl_b32 s8, s8, 1
	s_and_b32 s48, s8, 0xfe000
	v_or_b32_e32 v184, s15, v162
	v_mov_b32_e32 v185, v167
	v_lshlrev_b64 v[32:33], s95, v[184:185]
	s_or_b32 s8, s33, s48
	s_add_i32 s34, s56, 1
	v_lshlrev_b32_e32 v34, s95, v168
	v_lshl_add_u64 v[190:191], v[32:33], 0, s[8:9]
	v_cvt_f32_ubyte0_e32 v32, s34
	s_lshl_b32 s34, 1, s95
	v_add_u32_e32 v34, s8, v34
	v_mov_b32_e32 v35, v167
	s_and_b32 s90, s15, 0x1fc0
	v_exp_f32_e64 v44, -v32
	v_cvt_f32_u32_e32 v45, s34
	v_lshlrev_b64 v[32:33], 12, v[190:191]
	s_lshl_b32 s34, s56, 7
	v_lshlrev_b64 v[34:35], 12, v[34:35]
	v_lshl_add_u64 v[32:33], s[22:23], 0, v[32:33]
	s_mov_b32 s35, s9
	v_lshl_add_u64 v[34:35], s[22:23], 0, v[34:35]
	s_cmp_eq_u32 s93, 1
	v_lshl_add_u64 v[32:33], v[32:33], 0, s[34:35]
	v_lshl_add_u64 v[34:35], v[34:35], 0, s[34:35]
	s_cselect_b32 s8, s20, s26
	s_cselect_b32 s34, s21, s27
	s_cmp_eq_u32 s93, 0
	s_cselect_b32 s34, s54, s34
	s_cselect_b32 s8, s49, s8
	v_lshl_or_b32 v40, s56, 6, v164
	v_mov_b32_e32 v38, s8
	v_mov_b32_e32 v39, s34
	v_mul_i32_i24_e32 v40, 0x18000, v40
	v_mov_b32_e32 v41, v167
	v_lshl_add_u64 v[38:39], v[40:41], 1, v[38:39]
	s_lshl_b32 s8, s48, 1
	v_lshl_add_u64 v[38:39], v[38:39], 0, s[8:9]
	s_sub_i32 s8, 13, s95
	s_lshl_b32 s8, s33, s8
	s_mov_b32 s91, s9
	s_lshl_b32 s8, s8, 1
	s_lshl_b64 s[34:35], s[90:91], s95
	v_lshl_add_u64 v[36:37], v[34:35], 0, v[178:179]
	v_lshl_add_u64 v[38:39], v[38:39], 0, s[8:9]
	s_lshl_b64 s[34:35], s[34:35], 12
	v_lshl_add_u64 v[196:197], v[38:39], 0, v[178:179]
	v_lshl_add_u64 v[198:199], v[38:39], 0, v[180:181]
	v_lshl_add_u64 v[38:39], v[36:37], 0, s[34:35]
	s_or_b32 s34, s90, 4
	s_mov_b32 s35, s9
	s_lshl_b64 s[34:35], s[34:35], s95
	v_lshl_add_u64 v[34:35], v[34:35], 0, v[180:181]
	s_lshl_b64 s[34:35], s[34:35], 12
	s_lshl_b32 s8, s90, 1
	v_lshl_add_u64 v[40:41], v[34:35], 0, s[34:35]
	global_load_dwordx4 v[64:67], v[38:39], off offset:3072
	global_load_dwordx4 v[72:75], v[40:41], off offset:3072
	v_lshl_add_u64 v[38:39], v[196:197], 0, s[8:9]
	v_lshl_add_u64 v[40:41], v[198:199], 0, s[8:9]
	s_or_b32 s8, s90, 16
	v_add_co_u32_e32 v42, vcc, s1, v40
	s_lshl_b64 s[34:35], s[8:9], s95
	s_nop 0
	v_addc_co_u32_e32 v43, vcc, 0, v41, vcc
	s_lshl_b64 s[34:35], s[34:35], 12
	global_load_dwordx4 v[76:79], v[42:43], off
	v_lshl_add_u64 v[42:43], v[36:37], 0, s[34:35]
	s_or_b32 s8, s90, 20
	global_load_dwordx4 v[80:83], v[42:43], off offset:3072
	v_add_co_u32_e32 v42, vcc, s52, v38
	s_lshl_b64 s[34:35], s[8:9], s95
	s_nop 0
	v_addc_co_u32_e32 v43, vcc, 0, v39, vcc
	s_lshl_b64 s[34:35], s[34:35], 12
	global_load_dwordx4 v[84:87], v[42:43], off
	v_lshl_add_u64 v[42:43], v[34:35], 0, s[34:35]
	s_or_b32 s8, s15, 32
	global_load_dwordx4 v[88:91], v[42:43], off offset:3072
	v_add_co_u32_e32 v42, vcc, s53, v40
	s_lshl_b64 s[34:35], s[8:9], s95
	s_nop 0
	v_addc_co_u32_e32 v43, vcc, 0, v41, vcc
	s_lshl_b64 s[34:35], s[34:35], 12
	global_load_dwordx4 v[92:95], v[42:43], off
	v_lshl_add_u64 v[42:43], v[36:37], 0, s[34:35]
	s_or_b32 s8, s15, 36
	global_load_dwordx4 v[96:99], v[42:43], off offset:3072
	v_add_co_u32_e32 v42, vcc, s6, v38
	s_lshl_b64 s[34:35], s[8:9], s95
	s_nop 0
	v_addc_co_u32_e32 v43, vcc, 0, v39, vcc
	s_lshl_b64 s[34:35], s[34:35], 12
	s_or_b32 s8, s15, 48
	global_load_dwordx4 v[100:103], v[42:43], off
	v_lshl_add_u64 v[42:43], v[34:35], 0, s[34:35]
	s_lshl_b64 s[34:35], s[8:9], s95
	global_load_dwordx4 v[104:107], v[42:43], off offset:3072
	v_add_co_u32_e32 v42, vcc, s7, v40
	s_lshl_b64 s[34:35], s[34:35], 12
	s_or_b32 s8, s15, 52
	v_lshl_add_u64 v[192:193], v[36:37], 0, s[10:11]
	v_addc_co_u32_e32 v43, vcc, 0, v41, vcc
	v_lshl_add_u64 v[36:37], v[36:37], 0, s[34:35]
	s_lshl_b64 s[34:35], s[8:9], s95
	global_load_dwordx4 v[112:115], v[36:37], off offset:3072
	v_add_co_u32_e32 v36, vcc, s42, v38
	s_lshl_b64 s[34:35], s[34:35], 12
	v_lshl_add_u64 v[194:195], v[34:35], 0, s[10:11]
	v_addc_co_u32_e32 v37, vcc, 0, v39, vcc
	v_lshl_add_u64 v[34:35], v[34:35], 0, s[34:35]
	global_load_dwordx4 v[120:123], v[34:35], off offset:3072
	v_add_co_u32_e32 v34, vcc, 0xa80000, v40
	v_mov_b32_e32 v177, v167
	s_nop 0
	v_addc_co_u32_e32 v35, vcc, 0, v41, vcc
	v_lshl_add_u64 v[32:33], v[32:33], 0, v[176:177]
	global_load_dwordx4 v[68:71], v[38:39], off
	global_load_dwordx4 v[116:119], v[36:37], off
	global_load_dwordx4 v[108:111], v[42:43], off
	global_load_dwordx4 v[140:143], v[34:35], off
	global_load_dwordx4 v[144:147], v[32:33], off offset:2048
	global_load_dwordx4 v[148:151], v[32:33], off offset:2080
	global_load_dwordx4 v[152:155], v[32:33], off offset:2112
	global_load_dwordx4 v[156:159], v[32:33], off offset:2144
	v_mul_f32_e32 v32, 0x3fb8aa3b, v44
	s_lshr_b32 s34, 0x2000, s95
	v_mul_f32_e32 v177, v32, v45
